# G1 section B (conv outputs to LDS images) hand-written per wave-uniform role: scalar role branch instead of per-lane exec masks, token-pair v_pk_mul scaling in place
# baseline (speedup 1.0000x reference)
.LBB0_308:
	s_or_b64 exec, exec, s[44:45]
	v_lshrrev_b32_e32 v212, 4, v210
	s_waitcnt vmcnt(0) lgkmcnt(0)
	s_barrier
	s_and_saveexec_b64 s[8:9], s[38:39]
	s_cbranch_execz .LBB0_359
	v_readfirstlane_b32 s38, v188
	v_and_b32_e32 v44, 7, v212
	v_lshlrev_b32_e32 v102, 5, v44
	v_add_u32_e32 v102, 0x1f500, v102
	s_cmp_eq_u32 s38, 1
	s_cbranch_scc1 .Lg1b_k
	s_cmp_eq_u32 s38, 2
	s_cbranch_scc1 .Lg1b_v
	ds_read_b128 v[54:57], v102
	ds_read_b128 v[58:61], v102 offset:16
	v_and_b32_e32 v103, 3, v211
	v_lshrrev_b32_e32 v114, 2, v211
	v_lshlrev_b32_e32 v146, 1, v103
	v_and_b32_e32 v147, 1, v114
	v_xor_b32_e32 v146, v146, v147
	v_lshrrev_b32_e32 v115, 1, v44
	v_lshl_add_u32 v115, v115, 2, v114
	v_lshlrev_b32_e32 v115, 6, v115
	v_lshl_add_u32 v115, v103, 4, v115
	v_and_b32_e32 v147, 1, v44
	v_lshl_add_u32 v115, v147, 3, v115
	v_lshlrev_b32_e32 v115, 4, v115
	v_lshl_add_u32 v115, v146, 4, v115
	v_cvt_pk_bf16_f32 v46, v78, v104
	v_cvt_pk_bf16_f32 v47, v80, v106
	v_cvt_pk_bf16_f32 v48, v82, v108
	v_cvt_pk_bf16_f32 v49, v84, v118
	ds_write_b128 v115, v[46:49]
	v_cvt_pk_bf16_f32 v50, v79, v105
	v_cvt_pk_bf16_f32 v51, v81, v107
	v_cvt_pk_bf16_f32 v52, v83, v109
	v_cvt_pk_bf16_f32 v53, v85, v119
	v_xor_b32_e32 v147, 0x10, v115
	ds_write_b128 v147, v[50:53]
	v_cvt_pk_bf16_f32 v46, v90, v116
	v_cvt_pk_bf16_f32 v47, v86, v126
	v_cvt_pk_bf16_f32 v48, v88, v128
	v_cvt_pk_bf16_f32 v49, v92, v120
	v_xor_b32_e32 v146, 0x20, v115
	ds_write_b128 v146, v[46:49]
	v_cvt_pk_bf16_f32 v50, v91, v117
	v_cvt_pk_bf16_f32 v51, v87, v127
	v_cvt_pk_bf16_f32 v52, v89, v129
	v_cvt_pk_bf16_f32 v53, v93, v121
	v_xor_b32_e32 v147, 0x30, v115
	ds_write_b128 v147, v[50:53]
	v_cvt_pk_bf16_f32 v46, v96, v136
	v_cvt_pk_bf16_f32 v47, v94, v134
	v_cvt_pk_bf16_f32 v48, v98, v130
	v_cvt_pk_bf16_f32 v49, v100, v122
	v_xor_b32_e32 v146, 0x40, v115
	ds_write_b128 v146, v[46:49]
	v_cvt_pk_bf16_f32 v50, v97, v137
	v_cvt_pk_bf16_f32 v51, v95, v135
	v_cvt_pk_bf16_f32 v52, v99, v131
	v_cvt_pk_bf16_f32 v53, v101, v123
	v_xor_b32_e32 v147, 0x50, v115
	ds_write_b128 v147, v[50:53]
	v_cvt_pk_bf16_f32 v46, v70, v74
	v_cvt_pk_bf16_f32 v47, v76, v72
	v_cvt_pk_bf16_f32 v48, v112, v132
	v_cvt_pk_bf16_f32 v49, v110, v124
	v_xor_b32_e32 v146, 0x60, v115
	ds_write_b128 v146, v[46:49]
	v_cvt_pk_bf16_f32 v50, v71, v75
	v_cvt_pk_bf16_f32 v51, v77, v73
	v_cvt_pk_bf16_f32 v52, v113, v133
	v_cvt_pk_bf16_f32 v53, v111, v125
	v_xor_b32_e32 v147, 0x70, v115
	ds_write_b128 v147, v[50:53]
	v_mul_u32_u24_e32 v103, 0x880, v44
	v_lshl_add_u32 v103, v211, 4, v103
	v_add_u32_e32 v103, 0x10400, v103
	s_waitcnt lgkmcnt(8)
	v_pk_mul_f32 v[138:139], v[78:79], v[54:55]
	v_pk_mul_f32 v[140:141], v[104:105], v[54:55]
	v_pk_mul_f32 v[142:143], v[80:81], v[54:55]
	v_pk_mul_f32 v[144:145], v[106:107], v[54:55]
	v_cvt_pk_bf16_f32 v46, v138, v140
	v_cvt_pk_bf16_f32 v47, v142, v144
	v_cvt_pk_bf16_f32 v50, v139, v141
	v_cvt_pk_bf16_f32 v51, v143, v145
	v_pk_mul_f32 v[138:139], v[82:83], v[54:55]
	v_pk_mul_f32 v[140:141], v[108:109], v[54:55]
	v_pk_mul_f32 v[142:143], v[84:85], v[54:55]
	v_pk_mul_f32 v[144:145], v[118:119], v[54:55]
	v_cvt_pk_bf16_f32 v48, v138, v140
	v_cvt_pk_bf16_f32 v49, v142, v144
	v_cvt_pk_bf16_f32 v52, v139, v141
	v_cvt_pk_bf16_f32 v53, v143, v145
	ds_write_b128 v103, v[46:49]
	ds_write_b128 v103, v[50:53] offset:272
	v_pk_mul_f32 v[138:139], v[90:91], v[56:57]
	v_pk_mul_f32 v[140:141], v[116:117], v[56:57]
	v_pk_mul_f32 v[142:143], v[86:87], v[56:57]
	v_pk_mul_f32 v[144:145], v[126:127], v[56:57]
	v_cvt_pk_bf16_f32 v46, v138, v140
	v_cvt_pk_bf16_f32 v47, v142, v144
	v_cvt_pk_bf16_f32 v50, v139, v141
	v_cvt_pk_bf16_f32 v51, v143, v145
	v_pk_mul_f32 v[138:139], v[88:89], v[56:57]
	v_pk_mul_f32 v[140:141], v[128:129], v[56:57]
	v_pk_mul_f32 v[142:143], v[92:93], v[56:57]
	v_pk_mul_f32 v[144:145], v[120:121], v[56:57]
	v_cvt_pk_bf16_f32 v48, v138, v140
	v_cvt_pk_bf16_f32 v49, v142, v144
	v_cvt_pk_bf16_f32 v52, v139, v141
	v_cvt_pk_bf16_f32 v53, v143, v145
	ds_write_b128 v103, v[46:49] offset:544
	ds_write_b128 v103, v[50:53] offset:816
	v_pk_mul_f32 v[138:139], v[96:97], v[58:59]
	v_pk_mul_f32 v[140:141], v[136:137], v[58:59]
	v_pk_mul_f32 v[142:143], v[94:95], v[58:59]
	v_pk_mul_f32 v[144:145], v[134:135], v[58:59]
	v_cvt_pk_bf16_f32 v46, v138, v140
	v_cvt_pk_bf16_f32 v47, v142, v144
	v_cvt_pk_bf16_f32 v50, v139, v141
	v_cvt_pk_bf16_f32 v51, v143, v145
	v_pk_mul_f32 v[138:139], v[98:99], v[58:59]
	v_pk_mul_f32 v[140:141], v[130:131], v[58:59]
	v_pk_mul_f32 v[142:143], v[100:101], v[58:59]
	v_pk_mul_f32 v[144:145], v[122:123], v[58:59]
	v_cvt_pk_bf16_f32 v48, v138, v140
	v_cvt_pk_bf16_f32 v49, v142, v144
	v_cvt_pk_bf16_f32 v52, v139, v141
	v_cvt_pk_bf16_f32 v53, v143, v145
	ds_write_b128 v103, v[46:49] offset:1088
	ds_write_b128 v103, v[50:53] offset:1360
	v_pk_mul_f32 v[138:139], v[70:71], v[60:61]
	v_pk_mul_f32 v[140:141], v[74:75], v[60:61]
	v_pk_mul_f32 v[142:143], v[76:77], v[60:61]
	v_pk_mul_f32 v[144:145], v[72:73], v[60:61]
	v_cvt_pk_bf16_f32 v46, v138, v140
	v_cvt_pk_bf16_f32 v47, v142, v144
	v_cvt_pk_bf16_f32 v50, v139, v141
	v_cvt_pk_bf16_f32 v51, v143, v145
	v_pk_mul_f32 v[138:139], v[112:113], v[60:61]
	v_pk_mul_f32 v[140:141], v[132:133], v[60:61]
	v_pk_mul_f32 v[142:143], v[110:111], v[60:61]
	v_pk_mul_f32 v[144:145], v[124:125], v[60:61]
	v_cvt_pk_bf16_f32 v48, v138, v140
	v_cvt_pk_bf16_f32 v49, v142, v144
	v_cvt_pk_bf16_f32 v52, v139, v141
	v_cvt_pk_bf16_f32 v53, v143, v145
	ds_write_b128 v103, v[46:49] offset:1632
	ds_write_b128 v103, v[50:53] offset:1904
	s_branch .LBB0_359
.Lg1b_v:
	ds_read_b128 v[46:49], v102 offset:256
	ds_read_b128 v[50:53], v102 offset:272
	v_mul_u32_u24_e32 v103, 0x1080, v44
	v_lshl_add_u32 v103, v211, 4, v103
	v_add_u32_e32 v103, 0x8000, v103
	s_waitcnt lgkmcnt(0)
	v_pk_mul_f32 v[138:139], v[78:79], v[46:47]
	v_pk_mul_f32 v[140:141], v[104:105], v[46:47]
	v_pk_mul_f32 v[142:143], v[80:81], v[46:47]
	v_pk_mul_f32 v[144:145], v[106:107], v[46:47]
	v_cvt_pk_bf16_f32 v54, v138, v140
	v_cvt_pk_bf16_f32 v55, v142, v144
	v_cvt_pk_bf16_f32 v58, v139, v141
	v_cvt_pk_bf16_f32 v59, v143, v145
	v_pk_mul_f32 v[138:139], v[82:83], v[46:47]
	v_pk_mul_f32 v[140:141], v[108:109], v[46:47]
	v_pk_mul_f32 v[142:143], v[84:85], v[46:47]
	v_pk_mul_f32 v[144:145], v[118:119], v[46:47]
	v_cvt_pk_bf16_f32 v56, v138, v140
	v_cvt_pk_bf16_f32 v57, v142, v144
	v_cvt_pk_bf16_f32 v60, v139, v141
	v_cvt_pk_bf16_f32 v61, v143, v145
	ds_write_b128 v103, v[54:57]
	ds_write_b128 v103, v[58:61] offset:528
	v_pk_mul_f32 v[138:139], v[90:91], v[48:49]
	v_pk_mul_f32 v[140:141], v[116:117], v[48:49]
	v_pk_mul_f32 v[142:143], v[86:87], v[48:49]
	v_pk_mul_f32 v[144:145], v[126:127], v[48:49]
	v_cvt_pk_bf16_f32 v54, v138, v140
	v_cvt_pk_bf16_f32 v55, v142, v144
	v_cvt_pk_bf16_f32 v58, v139, v141
	v_cvt_pk_bf16_f32 v59, v143, v145
	v_pk_mul_f32 v[138:139], v[88:89], v[48:49]
	v_pk_mul_f32 v[140:141], v[128:129], v[48:49]
	v_pk_mul_f32 v[142:143], v[92:93], v[48:49]
	v_pk_mul_f32 v[144:145], v[120:121], v[48:49]
	v_cvt_pk_bf16_f32 v56, v138, v140
	v_cvt_pk_bf16_f32 v57, v142, v144
	v_cvt_pk_bf16_f32 v60, v139, v141
	v_cvt_pk_bf16_f32 v61, v143, v145
	ds_write_b128 v103, v[54:57] offset:1056
	ds_write_b128 v103, v[58:61] offset:1584
	v_pk_mul_f32 v[138:139], v[96:97], v[50:51]
	v_pk_mul_f32 v[140:141], v[136:137], v[50:51]
	v_pk_mul_f32 v[142:143], v[94:95], v[50:51]
	v_pk_mul_f32 v[144:145], v[134:135], v[50:51]
	v_cvt_pk_bf16_f32 v54, v138, v140
	v_cvt_pk_bf16_f32 v55, v142, v144
	v_cvt_pk_bf16_f32 v58, v139, v141
	v_cvt_pk_bf16_f32 v59, v143, v145
	v_pk_mul_f32 v[138:139], v[98:99], v[50:51]
	v_pk_mul_f32 v[140:141], v[130:131], v[50:51]
	v_pk_mul_f32 v[142:143], v[100:101], v[50:51]
	v_pk_mul_f32 v[144:145], v[122:123], v[50:51]
	v_cvt_pk_bf16_f32 v56, v138, v140
	v_cvt_pk_bf16_f32 v57, v142, v144
	v_cvt_pk_bf16_f32 v60, v139, v141
	v_cvt_pk_bf16_f32 v61, v143, v145
	ds_write_b128 v103, v[54:57] offset:2112
	ds_write_b128 v103, v[58:61] offset:2640
	v_pk_mul_f32 v[138:139], v[70:71], v[52:53]
	v_pk_mul_f32 v[140:141], v[74:75], v[52:53]
	v_pk_mul_f32 v[142:143], v[76:77], v[52:53]
	v_pk_mul_f32 v[144:145], v[72:73], v[52:53]
	v_cvt_pk_bf16_f32 v54, v138, v140
	v_cvt_pk_bf16_f32 v55, v142, v144
	v_cvt_pk_bf16_f32 v58, v139, v141
	v_cvt_pk_bf16_f32 v59, v143, v145
	v_pk_mul_f32 v[138:139], v[112:113], v[52:53]
	v_pk_mul_f32 v[140:141], v[132:133], v[52:53]
	v_pk_mul_f32 v[142:143], v[110:111], v[52:53]
	v_pk_mul_f32 v[144:145], v[124:125], v[52:53]
	v_cvt_pk_bf16_f32 v56, v138, v140
	v_cvt_pk_bf16_f32 v57, v142, v144
	v_cvt_pk_bf16_f32 v60, v139, v141
	v_cvt_pk_bf16_f32 v61, v143, v145
	ds_write_b128 v103, v[54:57] offset:3168
	ds_write_b128 v103, v[58:61] offset:3696
	s_branch .LBB0_359
.Lg1b_k:
	ds_read_b128 v[54:57], v102
	ds_read_b128 v[58:61], v102 offset:16
	ds_read_b128 v[46:49], v102 offset:256
	ds_read_b128 v[50:53], v102 offset:272
	ds_read_b128 v[62:65], v102 offset:512
	ds_read_b128 v[66:69], v102 offset:528
	v_and_b32_e32 v103, 3, v211
	v_lshrrev_b32_e32 v114, 2, v211
	v_lshlrev_b32_e32 v146, 1, v103
	v_and_b32_e32 v147, 1, v114
	v_xor_b32_e32 v146, v146, v147
	v_lshrrev_b32_e32 v115, 1, v44
	v_lshl_add_u32 v115, v115, 2, v114
	v_lshlrev_b32_e32 v115, 6, v115
	v_lshl_add_u32 v115, v103, 4, v115
	v_and_b32_e32 v147, 1, v44
	v_lshl_add_u32 v115, v147, 3, v115
	v_lshlrev_b32_e32 v115, 4, v115
	v_lshl_add_u32 v115, v146, 4, v115
	v_add_u32_e32 v115, 0x4000, v115
	v_cvt_pk_bf16_f32 v138, v78, v104
	v_cvt_pk_bf16_f32 v139, v80, v106
	v_cvt_pk_bf16_f32 v140, v82, v108
	v_cvt_pk_bf16_f32 v141, v84, v118
	ds_write_b128 v115, v[138:141]
	v_cvt_pk_bf16_f32 v142, v79, v105
	v_cvt_pk_bf16_f32 v143, v81, v107
	v_cvt_pk_bf16_f32 v144, v83, v109
	v_cvt_pk_bf16_f32 v145, v85, v119
	v_xor_b32_e32 v147, 0x10, v115
	ds_write_b128 v147, v[142:145]
	v_cvt_pk_bf16_f32 v138, v90, v116
	v_cvt_pk_bf16_f32 v139, v86, v126
	v_cvt_pk_bf16_f32 v140, v88, v128
	v_cvt_pk_bf16_f32 v141, v92, v120
	v_xor_b32_e32 v146, 0x20, v115
	ds_write_b128 v146, v[138:141]
	v_cvt_pk_bf16_f32 v142, v91, v117
	v_cvt_pk_bf16_f32 v143, v87, v127
	v_cvt_pk_bf16_f32 v144, v89, v129
	v_cvt_pk_bf16_f32 v145, v93, v121
	v_xor_b32_e32 v147, 0x30, v115
	ds_write_b128 v147, v[142:145]
	v_cvt_pk_bf16_f32 v138, v96, v136
	v_cvt_pk_bf16_f32 v139, v94, v134
	v_cvt_pk_bf16_f32 v140, v98, v130
	v_cvt_pk_bf16_f32 v141, v100, v122
	v_xor_b32_e32 v146, 0x40, v115
	ds_write_b128 v146, v[138:141]
	v_cvt_pk_bf16_f32 v142, v97, v137
	v_cvt_pk_bf16_f32 v143, v95, v135
	v_cvt_pk_bf16_f32 v144, v99, v131
	v_cvt_pk_bf16_f32 v145, v101, v123
	v_xor_b32_e32 v147, 0x50, v115
	ds_write_b128 v147, v[142:145]
	v_cvt_pk_bf16_f32 v138, v70, v74
	v_cvt_pk_bf16_f32 v139, v76, v72
	v_cvt_pk_bf16_f32 v140, v112, v132
	v_cvt_pk_bf16_f32 v141, v110, v124
	v_xor_b32_e32 v146, 0x60, v115
	ds_write_b128 v146, v[138:141]
	v_cvt_pk_bf16_f32 v142, v71, v75
	v_cvt_pk_bf16_f32 v143, v77, v73
	v_cvt_pk_bf16_f32 v144, v113, v133
	v_cvt_pk_bf16_f32 v145, v111, v125
	v_xor_b32_e32 v147, 0x70, v115
	ds_write_b128 v147, v[142:145]
	v_mul_u32_u24_e32 v103, 0x1080, v44
	v_lshl_add_u32 v103, v211, 4, v103
	v_add_u32_e32 v103, 0x8100, v103
	s_waitcnt lgkmcnt(8)
	v_pk_mul_f32 v[46:47], v[46:47], v[54:55]
	v_pk_mul_f32 v[48:49], v[48:49], v[56:57]
	v_pk_mul_f32 v[50:51], v[50:51], v[58:59]
	v_pk_mul_f32 v[52:53], v[52:53], v[60:61]
	v_and_b32_e32 v114, 7, v211
	v_xor_b32_e32 v114, v114, v44
	v_mul_u32_u24_e32 v115, 0x480, v211
	v_lshl_add_u32 v114, v114, 4, v115
	v_add_u32_e32 v114, 0x14800, v114
	v_pk_mul_f32 v[138:139], v[78:79], v[46:47]
	v_pk_mul_f32 v[140:141], v[104:105], v[46:47]
	v_pk_mul_f32 v[142:143], v[80:81], v[46:47]
	v_pk_mul_f32 v[144:145], v[106:107], v[46:47]
	v_cvt_pk_bf16_f32 v54, v138, v140
	v_cvt_pk_bf16_f32 v55, v142, v144
	v_cvt_pk_bf16_f32 v58, v139, v141
	v_cvt_pk_bf16_f32 v59, v143, v145
	v_pk_mul_f32 v[138:139], v[82:83], v[46:47]
	v_pk_mul_f32 v[140:141], v[108:109], v[46:47]
	v_pk_mul_f32 v[142:143], v[84:85], v[46:47]
	v_pk_mul_f32 v[144:145], v[118:119], v[46:47]
	v_cvt_pk_bf16_f32 v56, v138, v140
	v_cvt_pk_bf16_f32 v57, v142, v144
	v_cvt_pk_bf16_f32 v60, v139, v141
	v_cvt_pk_bf16_f32 v61, v143, v145
	ds_write_b128 v103, v[54:57]
	ds_write_b128 v103, v[58:61] offset:528
	v_pk_mul_f32 v[138:139], v[90:91], v[48:49]
	v_pk_mul_f32 v[140:141], v[116:117], v[48:49]
	v_pk_mul_f32 v[142:143], v[86:87], v[48:49]
	v_pk_mul_f32 v[144:145], v[126:127], v[48:49]
	v_cvt_pk_bf16_f32 v54, v138, v140
	v_cvt_pk_bf16_f32 v55, v142, v144
	v_cvt_pk_bf16_f32 v58, v139, v141
	v_cvt_pk_bf16_f32 v59, v143, v145
	v_pk_mul_f32 v[138:139], v[88:89], v[48:49]
	v_pk_mul_f32 v[140:141], v[128:129], v[48:49]
	v_pk_mul_f32 v[142:143], v[92:93], v[48:49]
	v_pk_mul_f32 v[144:145], v[120:121], v[48:49]
	v_cvt_pk_bf16_f32 v56, v138, v140
	v_cvt_pk_bf16_f32 v57, v142, v144
	v_cvt_pk_bf16_f32 v60, v139, v141
	v_cvt_pk_bf16_f32 v61, v143, v145
	ds_write_b128 v103, v[54:57] offset:1056
	ds_write_b128 v103, v[58:61] offset:1584
	v_pk_mul_f32 v[138:139], v[96:97], v[50:51]
	v_pk_mul_f32 v[140:141], v[136:137], v[50:51]
	v_pk_mul_f32 v[142:143], v[94:95], v[50:51]
	v_pk_mul_f32 v[144:145], v[134:135], v[50:51]
	v_cvt_pk_bf16_f32 v54, v138, v140
	v_cvt_pk_bf16_f32 v55, v142, v144
	v_cvt_pk_bf16_f32 v58, v139, v141
	v_cvt_pk_bf16_f32 v59, v143, v145
	v_pk_mul_f32 v[138:139], v[98:99], v[50:51]
	v_pk_mul_f32 v[140:141], v[130:131], v[50:51]
	v_pk_mul_f32 v[142:143], v[100:101], v[50:51]
	v_pk_mul_f32 v[144:145], v[122:123], v[50:51]
	v_cvt_pk_bf16_f32 v56, v138, v140
	v_cvt_pk_bf16_f32 v57, v142, v144
	v_cvt_pk_bf16_f32 v60, v139, v141
	v_cvt_pk_bf16_f32 v61, v143, v145
	ds_write_b128 v103, v[54:57] offset:2112
	ds_write_b128 v103, v[58:61] offset:2640
	v_pk_mul_f32 v[138:139], v[70:71], v[52:53]
	v_pk_mul_f32 v[140:141], v[74:75], v[52:53]
	v_pk_mul_f32 v[142:143], v[76:77], v[52:53]
	v_pk_mul_f32 v[144:145], v[72:73], v[52:53]
	v_cvt_pk_bf16_f32 v54, v138, v140
	v_cvt_pk_bf16_f32 v55, v142, v144
	v_cvt_pk_bf16_f32 v58, v139, v141
	v_cvt_pk_bf16_f32 v59, v143, v145
	v_pk_mul_f32 v[138:139], v[112:113], v[52:53]
	v_pk_mul_f32 v[140:141], v[132:133], v[52:53]
	v_pk_mul_f32 v[142:143], v[110:111], v[52:53]
	v_pk_mul_f32 v[144:145], v[124:125], v[52:53]
	v_cvt_pk_bf16_f32 v56, v138, v140
	v_cvt_pk_bf16_f32 v57, v142, v144
	v_cvt_pk_bf16_f32 v60, v139, v141
	v_cvt_pk_bf16_f32 v61, v143, v145
	ds_write_b128 v103, v[54:57] offset:3168
	ds_write_b128 v103, v[58:61] offset:3696
	v_pk_mul_f32 v[138:139], v[78:79], v[62:63]
	v_pk_mul_f32 v[140:141], v[90:91], v[64:65]
	v_pk_mul_f32 v[142:143], v[96:97], v[66:67]
	v_pk_mul_f32 v[144:145], v[70:71], v[68:69]
	v_cvt_pk_bf16_f32 v54, v138, v139
	v_cvt_pk_bf16_f32 v55, v140, v141
	v_cvt_pk_bf16_f32 v56, v142, v143
	v_cvt_pk_bf16_f32 v57, v144, v145
	ds_write_b128 v114, v[54:57]
	v_pk_mul_f32 v[138:139], v[104:105], v[62:63]
	v_pk_mul_f32 v[140:141], v[116:117], v[64:65]
	v_pk_mul_f32 v[142:143], v[136:137], v[66:67]
	v_pk_mul_f32 v[144:145], v[74:75], v[68:69]
	v_cvt_pk_bf16_f32 v58, v138, v139
	v_cvt_pk_bf16_f32 v59, v140, v141
	v_cvt_pk_bf16_f32 v60, v142, v143
	v_cvt_pk_bf16_f32 v61, v144, v145
	ds_write_b128 v114, v[58:61] offset:144
	v_pk_mul_f32 v[138:139], v[80:81], v[62:63]
	v_pk_mul_f32 v[140:141], v[86:87], v[64:65]
	v_pk_mul_f32 v[142:143], v[94:95], v[66:67]
	v_pk_mul_f32 v[144:145], v[76:77], v[68:69]
	v_cvt_pk_bf16_f32 v54, v138, v139
	v_cvt_pk_bf16_f32 v55, v140, v141
	v_cvt_pk_bf16_f32 v56, v142, v143
	v_cvt_pk_bf16_f32 v57, v144, v145
	ds_write_b128 v114, v[54:57] offset:288
	v_pk_mul_f32 v[138:139], v[106:107], v[62:63]
	v_pk_mul_f32 v[140:141], v[126:127], v[64:65]
	v_pk_mul_f32 v[142:143], v[134:135], v[66:67]
	v_pk_mul_f32 v[144:145], v[72:73], v[68:69]
	v_cvt_pk_bf16_f32 v58, v138, v139
	v_cvt_pk_bf16_f32 v59, v140, v141
	v_cvt_pk_bf16_f32 v60, v142, v143
	v_cvt_pk_bf16_f32 v61, v144, v145
	ds_write_b128 v114, v[58:61] offset:432
	v_pk_mul_f32 v[138:139], v[82:83], v[62:63]
	v_pk_mul_f32 v[140:141], v[88:89], v[64:65]
	v_pk_mul_f32 v[142:143], v[98:99], v[66:67]
	v_pk_mul_f32 v[144:145], v[112:113], v[68:69]
	v_cvt_pk_bf16_f32 v54, v138, v139
	v_cvt_pk_bf16_f32 v55, v140, v141
	v_cvt_pk_bf16_f32 v56, v142, v143
	v_cvt_pk_bf16_f32 v57, v144, v145
	ds_write_b128 v114, v[54:57] offset:576
	v_pk_mul_f32 v[138:139], v[108:109], v[62:63]
	v_pk_mul_f32 v[140:141], v[128:129], v[64:65]
	v_pk_mul_f32 v[142:143], v[130:131], v[66:67]
	v_pk_mul_f32 v[144:145], v[132:133], v[68:69]
	v_cvt_pk_bf16_f32 v58, v138, v139
	v_cvt_pk_bf16_f32 v59, v140, v141
	v_cvt_pk_bf16_f32 v60, v142, v143
	v_cvt_pk_bf16_f32 v61, v144, v145
	ds_write_b128 v114, v[58:61] offset:720
	v_pk_mul_f32 v[138:139], v[84:85], v[62:63]
	v_pk_mul_f32 v[140:141], v[92:93], v[64:65]
	v_pk_mul_f32 v[142:143], v[100:101], v[66:67]
	v_pk_mul_f32 v[144:145], v[110:111], v[68:69]
	v_cvt_pk_bf16_f32 v54, v138, v139
	v_cvt_pk_bf16_f32 v55, v140, v141
	v_cvt_pk_bf16_f32 v56, v142, v143
	v_cvt_pk_bf16_f32 v57, v144, v145
	ds_write_b128 v114, v[54:57] offset:864
	v_pk_mul_f32 v[138:139], v[118:119], v[62:63]
	v_pk_mul_f32 v[140:141], v[120:121], v[64:65]
	v_pk_mul_f32 v[142:143], v[122:123], v[66:67]
	v_pk_mul_f32 v[144:145], v[124:125], v[68:69]
	v_cvt_pk_bf16_f32 v58, v138, v139
	v_cvt_pk_bf16_f32 v59, v140, v141
	v_cvt_pk_bf16_f32 v60, v142, v143
	v_cvt_pk_bf16_f32 v61, v144, v145
	ds_write_b128 v114, v[58:61] offset:1008
